# v12 + s_setprio 1 around the QK^T MFMA burst of the hand-written diff-attention loop (s_setprio 0 after)
# speedup vs baseline: 1.0117x; 1.0005x over previous
.Ldq0_addr:
	s_and_b32 s23, s42, 1
	s_mul_i32 s0, s23, 0x4400
	v_add_u32_e32 v205, s0, v173
	s_mul_i32 s0, s23, 0x4800
	v_add_u32_e32 v206, s0, v174
	s_xor_b32 s22, s23, 1
	s_mul_i32 s0, s22, 0x4400
	s_mul_i32 s22, s22, 0x4800
	global_load_dwordx4 v[212:215], v2, s[24:25]
	global_load_dwordx4 v[216:219], v244, s[20:21]
	global_load_dwordx4 v[220:223], v160, s[24:25]
	global_load_dwordx4 v[224:227], v245, s[20:21]
	global_load_dwordx4 v[228:231], v158, s[24:25]
	global_load_dwordx4 v[232:235], v246, s[20:21]
	global_load_dwordx4 v[236:239], v156, s[24:25]
	global_load_dwordx4 v[240:243], v249, s[20:21]
	ds_read_b128 v[4:7], v205
	ds_read_b128 v[8:11], v205 offset:8704
	ds_read_b128 v[14:17], v205 offset:32
	ds_read_b128 v[208:211], v205 offset:8736
	s_waitcnt vmcnt(8)
	s_setprio 1
	s_waitcnt lgkmcnt(3)
	v_mfma_f32_32x32x16_bf16 v[98:113], v[4:7], v[126:129], 0
	ds_read_b128 v[252:255], v205 offset:64
	s_waitcnt lgkmcnt(3)
	v_mfma_f32_32x32x16_bf16 v[82:97], v[8:11], v[126:129], 0
	ds_read_b128 v[4:7], v205 offset:8768
	s_waitcnt lgkmcnt(3)
	v_mfma_f32_32x32x16_bf16 v[98:113], v[14:17], v[122:125], v[98:113]
	ds_read_b128 v[8:11], v205 offset:96
	s_waitcnt lgkmcnt(3)
	v_mfma_f32_32x32x16_bf16 v[82:97], v[208:211], v[122:125], v[82:97]
	ds_read_b128 v[14:17], v205 offset:8800
	s_waitcnt lgkmcnt(3)
	v_mfma_f32_32x32x16_bf16 v[98:113], v[252:255], v[118:121], v[98:113]
	ds_read_b128 v[208:211], v206 offset:34816
	s_waitcnt lgkmcnt(3)
	v_mfma_f32_32x32x16_bf16 v[82:97], v[4:7], v[118:121], v[82:97]
	ds_read_b128 v[252:255], v206 offset:39424
	s_waitcnt lgkmcnt(3)
	v_mfma_f32_32x32x16_bf16 v[98:113], v[8:11], v[114:117], v[98:113]
	ds_read_b128 v[4:7], v206 offset:44032
	s_waitcnt lgkmcnt(3)
	v_mfma_f32_32x32x16_bf16 v[82:97], v[14:17], v[114:117], v[82:97]
	ds_read_b128 v[8:11], v206 offset:48640
	s_setprio 0
	v_add_f32_e32 v159, 0x41000000, v149
	s_nop 6
	v_max3_f32 v207, v98, v99, v100
	v_max3_f32 v13, v101, v102, v103
	v_max3_f32 v207, v207, v104, v105
	v_max3_f32 v13, v13, v106, v107
	v_max3_f32 v207, v207, v108, v109
	v_max3_f32 v13, v13, v110, v111
	v_max3_f32 v207, v207, v112, v113
	v_max3_f32 v13, v13, v82, v83
	v_max3_f32 v207, v207, v84, v85
	v_max3_f32 v13, v13, v86, v87
	v_max3_f32 v207, v207, v88, v89
	v_max3_f32 v13, v13, v90, v91
	v_max3_f32 v207, v207, v92, v93
	v_max3_f32 v13, v13, v94, v95
	v_max3_f32 v207, v207, v96, v97
	v_max_f32_e32 v207, v207, v13
	v_mov_b32_e32 v13, v207
	s_nop 1
	v_permlane32_swap_b32_e32 v207, v13
	v_max_f32_e32 v207, v207, v13
	v_cmp_gt_f32_e32 vcc, v207, v159
	s_cbranch_vccz .Ldq0_nores
	v_max_f32_e32 v207, v149, v207
	v_sub_f32_e32 v250, v149, v207
	v_exp_f32_e32 v250, v250
	v_mov_b32_e32 v149, v207
	v_pk_mul_f32 v[66:67], v[66:67], v[250:251] op_sel_hi:[1,0]
	v_pk_mul_f32 v[68:69], v[68:69], v[250:251] op_sel_hi:[1,0]
	v_pk_mul_f32 v[70:71], v[70:71], v[250:251] op_sel_hi:[1,0]
	v_pk_mul_f32 v[72:73], v[72:73], v[250:251] op_sel_hi:[1,0]
	v_pk_mul_f32 v[74:75], v[74:75], v[250:251] op_sel_hi:[1,0]
	v_pk_mul_f32 v[76:77], v[76:77], v[250:251] op_sel_hi:[1,0]
	v_pk_mul_f32 v[78:79], v[78:79], v[250:251] op_sel_hi:[1,0]
	v_pk_mul_f32 v[80:81], v[80:81], v[250:251] op_sel_hi:[1,0]
	v_pk_mul_f32 v[50:51], v[50:51], v[250:251] op_sel_hi:[1,0]
	v_pk_mul_f32 v[52:53], v[52:53], v[250:251] op_sel_hi:[1,0]
	v_pk_mul_f32 v[54:55], v[54:55], v[250:251] op_sel_hi:[1,0]
	v_pk_mul_f32 v[56:57], v[56:57], v[250:251] op_sel_hi:[1,0]
	v_pk_mul_f32 v[58:59], v[58:59], v[250:251] op_sel_hi:[1,0]
	v_pk_mul_f32 v[60:61], v[60:61], v[250:251] op_sel_hi:[1,0]
	v_pk_mul_f32 v[62:63], v[62:63], v[250:251] op_sel_hi:[1,0]
	v_pk_mul_f32 v[64:65], v[64:65], v[250:251] op_sel_hi:[1,0]
	v_pk_mul_f32 v[34:35], v[34:35], v[250:251] op_sel_hi:[1,0]
	v_pk_mul_f32 v[36:37], v[36:37], v[250:251] op_sel_hi:[1,0]
	v_pk_mul_f32 v[38:39], v[38:39], v[250:251] op_sel_hi:[1,0]
	v_pk_mul_f32 v[40:41], v[40:41], v[250:251] op_sel_hi:[1,0]
	v_pk_mul_f32 v[42:43], v[42:43], v[250:251] op_sel_hi:[1,0]
	v_pk_mul_f32 v[44:45], v[44:45], v[250:251] op_sel_hi:[1,0]
	v_pk_mul_f32 v[46:47], v[46:47], v[250:251] op_sel_hi:[1,0]
	v_pk_mul_f32 v[48:49], v[48:49], v[250:251] op_sel_hi:[1,0]
	v_pk_mul_f32 v[18:19], v[18:19], v[250:251] op_sel_hi:[1,0]
	v_pk_mul_f32 v[20:21], v[20:21], v[250:251] op_sel_hi:[1,0]
	v_pk_mul_f32 v[22:23], v[22:23], v[250:251] op_sel_hi:[1,0]
	v_pk_mul_f32 v[24:25], v[24:25], v[250:251] op_sel_hi:[1,0]
	v_pk_mul_f32 v[26:27], v[26:27], v[250:251] op_sel_hi:[1,0]
	v_pk_mul_f32 v[28:29], v[28:29], v[250:251] op_sel_hi:[1,0]
	v_pk_mul_f32 v[30:31], v[30:31], v[250:251] op_sel_hi:[1,0]
	v_pk_mul_f32 v[32:33], v[32:33], v[250:251] op_sel_hi:[1,0]
	v_mul_f32_e32 v12, v12, v250
	v_mul_f32_e32 v157, v157, v250

.Ldq1_addr:
	s_and_b32 s23, s42, 1
	s_mul_i32 s0, s23, 0x4400
	v_add_u32_e32 v207, s0, v174
	s_mul_i32 s0, s23, 0x4800
	v_add_u32_e32 v163, s0, v175
	s_xor_b32 s22, s23, 1
	s_mul_i32 s0, s22, 0x4400
	s_mul_i32 s22, s22, 0x4800
	global_load_dwordx4 v[212:215], v2, s[24:25]
	global_load_dwordx4 v[216:219], v244, s[20:21]
	global_load_dwordx4 v[220:223], v162, s[24:25]
	global_load_dwordx4 v[224:227], v245, s[20:21]
	global_load_dwordx4 v[228:231], v160, s[24:25]
	global_load_dwordx4 v[232:235], v246, s[20:21]
	global_load_dwordx4 v[236:239], v158, s[24:25]
	global_load_dwordx4 v[240:243], v249, s[20:21]
	ds_read_b128 v[4:7], v207
	ds_read_b128 v[8:11], v207 offset:8704
	ds_read_b128 v[14:17], v207 offset:32
	ds_read_b128 v[208:211], v207 offset:8736
	s_waitcnt vmcnt(8)
	s_setprio 1
	s_waitcnt lgkmcnt(3)
	v_mfma_f32_32x32x16_bf16 v[98:113], v[4:7], v[126:129], 0
	ds_read_b128 v[252:255], v207 offset:64
	s_waitcnt lgkmcnt(3)
	v_mfma_f32_32x32x16_bf16 v[82:97], v[8:11], v[126:129], 0
	ds_read_b128 v[4:7], v207 offset:8768
	s_waitcnt lgkmcnt(3)
	v_mfma_f32_32x32x16_bf16 v[98:113], v[14:17], v[122:125], v[98:113]
	ds_read_b128 v[8:11], v207 offset:96
	s_waitcnt lgkmcnt(3)
	v_mfma_f32_32x32x16_bf16 v[82:97], v[208:211], v[122:125], v[82:97]
	ds_read_b128 v[14:17], v207 offset:8800
	s_waitcnt lgkmcnt(3)
	v_mfma_f32_32x32x16_bf16 v[98:113], v[252:255], v[118:121], v[98:113]
	ds_read_b128 v[208:211], v163 offset:34816
	s_waitcnt lgkmcnt(3)
	v_mfma_f32_32x32x16_bf16 v[82:97], v[4:7], v[118:121], v[82:97]
	ds_read_b128 v[252:255], v163 offset:39424
	s_waitcnt lgkmcnt(3)
	v_mfma_f32_32x32x16_bf16 v[98:113], v[8:11], v[114:117], v[98:113]
	ds_read_b128 v[4:7], v163 offset:44032
	s_waitcnt lgkmcnt(3)
	v_mfma_f32_32x32x16_bf16 v[82:97], v[14:17], v[114:117], v[82:97]
	ds_read_b128 v[8:11], v163 offset:48640
	s_setprio 0
	v_add_f32_e32 v161, 0x41000000, v151
	s_nop 6
	v_max3_f32 v251, v98, v99, v100
	v_max3_f32 v13, v101, v102, v103
	v_max3_f32 v251, v251, v104, v105
	v_max3_f32 v13, v13, v106, v107
	v_max3_f32 v251, v251, v108, v109
	v_max3_f32 v13, v13, v110, v111
	v_max3_f32 v251, v251, v112, v113
	v_max3_f32 v13, v13, v82, v83
	v_max3_f32 v251, v251, v84, v85
	v_max3_f32 v13, v13, v86, v87
	v_max3_f32 v251, v251, v88, v89
	v_max3_f32 v13, v13, v90, v91
	v_max3_f32 v251, v251, v92, v93
	v_max3_f32 v13, v13, v94, v95
	v_max3_f32 v251, v251, v96, v97
	v_max_f32_e32 v251, v251, v13
	v_mov_b32_e32 v13, v251
	s_nop 1
	v_permlane32_swap_b32_e32 v251, v13
	v_max_f32_e32 v251, v251, v13
	v_cmp_gt_f32_e32 vcc, v251, v161
	s_cbranch_vccz .Ldq1_nores
	v_max_f32_e32 v251, v151, v251
	v_sub_f32_e32 v250, v151, v251
	v_exp_f32_e32 v250, v250
	v_mov_b32_e32 v151, v251
	v_pk_mul_f32 v[66:67], v[66:67], v[250:251] op_sel_hi:[1,0]
	v_pk_mul_f32 v[68:69], v[68:69], v[250:251] op_sel_hi:[1,0]
	v_pk_mul_f32 v[70:71], v[70:71], v[250:251] op_sel_hi:[1,0]
	v_pk_mul_f32 v[72:73], v[72:73], v[250:251] op_sel_hi:[1,0]
	v_pk_mul_f32 v[74:75], v[74:75], v[250:251] op_sel_hi:[1,0]
	v_pk_mul_f32 v[76:77], v[76:77], v[250:251] op_sel_hi:[1,0]
	v_pk_mul_f32 v[78:79], v[78:79], v[250:251] op_sel_hi:[1,0]
	v_pk_mul_f32 v[80:81], v[80:81], v[250:251] op_sel_hi:[1,0]
	v_pk_mul_f32 v[50:51], v[50:51], v[250:251] op_sel_hi:[1,0]
	v_pk_mul_f32 v[52:53], v[52:53], v[250:251] op_sel_hi:[1,0]
	v_pk_mul_f32 v[54:55], v[54:55], v[250:251] op_sel_hi:[1,0]
	v_pk_mul_f32 v[56:57], v[56:57], v[250:251] op_sel_hi:[1,0]
	v_pk_mul_f32 v[58:59], v[58:59], v[250:251] op_sel_hi:[1,0]
	v_pk_mul_f32 v[60:61], v[60:61], v[250:251] op_sel_hi:[1,0]
	v_pk_mul_f32 v[62:63], v[62:63], v[250:251] op_sel_hi:[1,0]
	v_pk_mul_f32 v[64:65], v[64:65], v[250:251] op_sel_hi:[1,0]
	v_pk_mul_f32 v[34:35], v[34:35], v[250:251] op_sel_hi:[1,0]
	v_pk_mul_f32 v[36:37], v[36:37], v[250:251] op_sel_hi:[1,0]
	v_pk_mul_f32 v[38:39], v[38:39], v[250:251] op_sel_hi:[1,0]
	v_pk_mul_f32 v[40:41], v[40:41], v[250:251] op_sel_hi:[1,0]
	v_pk_mul_f32 v[42:43], v[42:43], v[250:251] op_sel_hi:[1,0]
	v_pk_mul_f32 v[44:45], v[44:45], v[250:251] op_sel_hi:[1,0]
	v_pk_mul_f32 v[46:47], v[46:47], v[250:251] op_sel_hi:[1,0]
	v_pk_mul_f32 v[48:49], v[48:49], v[250:251] op_sel_hi:[1,0]
	v_pk_mul_f32 v[18:19], v[18:19], v[250:251] op_sel_hi:[1,0]
	v_pk_mul_f32 v[20:21], v[20:21], v[250:251] op_sel_hi:[1,0]
	v_pk_mul_f32 v[22:23], v[22:23], v[250:251] op_sel_hi:[1,0]
	v_pk_mul_f32 v[24:25], v[24:25], v[250:251] op_sel_hi:[1,0]
	v_pk_mul_f32 v[26:27], v[26:27], v[250:251] op_sel_hi:[1,0]
	v_pk_mul_f32 v[28:29], v[28:29], v[250:251] op_sel_hi:[1,0]
	v_pk_mul_f32 v[30:31], v[30:31], v[250:251] op_sel_hi:[1,0]
	v_pk_mul_f32 v[32:33], v[32:33], v[250:251] op_sel_hi:[1,0]
	v_mul_f32_e32 v12, v12, v250
	v_mul_f32_e32 v159, v159, v250
